# v36 + nt on P13 fused-final phase-1 x loads (read once, then overwritten by the output)
# baseline (speedup 1.0000x reference)
.LBB0_3464:
	v_lshlrev_b32_e32 v130, 3, v153
	s_lshl_b32 s3, s10, 8
	s_lshl_b32 s4, s53, 8
	v_lshl_or_b32 v130, s11, 5, v130
	v_or_b32_e32 v132, s4, v130
	v_add_u32_e32 v130, s3, v1
	v_ashrrev_i32_e32 v131, 31, v130
	v_lshlrev_b64 v[130:131], 12, v[130:131]
	v_lshl_add_u64 v[130:131], s[26:27], 0, v[130:131]
	v_ashrrev_i32_e32 v133, 31, v132
	v_lshl_add_u64 v[130:131], v[132:133], 2, v[130:131]
	s_waitcnt vmcnt(0)
	s_setprio 0
	s_barrier
	global_load_dwordx4 v[134:137], v[130:131], off nt
	global_load_dwordx4 v[142:145], v[130:131], off offset:16 nt
	global_load_dwordx4 v[146:149], v[130:131], off offset:512 nt
	global_load_dwordx4 v[154:157], v[130:131], off offset:528 nt
	v_mbcnt_lo_u32_b32 v138, -1, 0
	v_mbcnt_hi_u32_b32 v138, -1, v138
	v_and_b32_e32 v150, 64, v138
	v_xor_b32_e32 v139, 16, v138
	v_add_u32_e32 v151, 64, v150
	v_cmp_lt_i32_e32 vcc, v139, v151
	s_lshl_b32 s0, s11, 2
	s_add_i32 s5, s0, 0
	v_cndmask_b32_e32 v139, v138, v139, vcc
	v_lshlrev_b32_e32 v150, 2, v139
	s_waitcnt vmcnt(0)
	v_pk_fma_f32 v[128:129], v[128:129], 0.5, v[136:137] op_sel_hi:[1,0,1]
	v_pk_fma_f32 v[134:135], v[126:127], 0.5, v[134:135] op_sel_hi:[1,0,1]
	v_pk_fma_f32 v[124:125], v[124:125], 0.5, v[144:145] op_sel_hi:[1,0,1]
	v_pk_fma_f32 v[126:127], v[122:123], 0.5, v[142:143] op_sel_hi:[1,0,1]
	v_pk_fma_f32 v[120:121], v[120:121], 0.5, v[148:149] op_sel_hi:[1,0,1]
	v_pk_fma_f32 v[122:123], v[118:119], 0.5, v[146:147] op_sel_hi:[1,0,1]
	v_pk_fma_f32 v[116:117], v[116:117], 0.5, v[156:157] op_sel_hi:[1,0,1]
	v_pk_fma_f32 v[118:119], v[114:115], 0.5, v[154:155] op_sel_hi:[1,0,1]
	v_mul_f32_e32 v114, v135, v135
	v_mul_f32_e32 v115, v129, v129
	v_mul_f32_e32 v136, v127, v127
	v_mul_f32_e32 v137, v125, v125
	v_mul_f32_e32 v139, v123, v123
	v_mul_f32_e32 v142, v121, v121
	v_mul_f32_e32 v143, v119, v119
	v_mul_f32_e32 v144, v117, v117
	v_fmac_f32_e32 v114, v134, v134
	v_fmac_f32_e32 v115, v128, v128
	v_fmac_f32_e32 v136, v126, v126
	v_fmac_f32_e32 v137, v124, v124
	v_fmac_f32_e32 v139, v122, v122
	v_fmac_f32_e32 v142, v120, v120
	v_fmac_f32_e32 v143, v118, v118
	v_fmac_f32_e32 v144, v116, v116
	v_add_f32_e32 v114, v114, v115
	v_add_f32_e32 v115, v136, v137
	v_add_f32_e32 v136, v139, v142
	v_add_f32_e32 v137, v143, v144
	v_add_f32_e32 v114, v114, v115
	v_add_f32_e32 v115, v136, v137
	v_add_f32_e32 v114, v114, v115
	ds_bpermute_b32 v115, v150, v114
	v_xor_b32_e32 v136, 32, v138
	v_cmp_lt_i32_e32 vcc, v136, v151
	s_waitcnt lgkmcnt(0)
	v_add_f32_e32 v114, v114, v115
	v_cndmask_b32_e32 v136, v138, v136, vcc
	v_lshlrev_b32_e32 v151, 2, v136
	ds_bpermute_b32 v115, v151, v114
	v_cmp_eq_u32_e32 vcc, 0, v153
	s_and_saveexec_b64 s[0:1], vcc
	s_cbranch_execz .LBB0_3466
	v_lshl_add_u32 v136, v1, 4, s5
	s_waitcnt lgkmcnt(0)
	v_add_f32_e32 v114, v114, v115
	ds_write_b32 v136, v114
.LBB0_3466:
	s_or_b64 exec, exec, s[0:1]
	v_or_b32_e32 v138, 16, v1
	v_add_u32_e32 v114, s3, v138
	s_waitcnt lgkmcnt(0)
	v_ashrrev_i32_e32 v115, 31, v114
	v_lshlrev_b64 v[114:115], 12, v[114:115]
	v_lshl_add_u64 v[114:115], s[26:27], 0, v[114:115]
	v_lshl_add_u64 v[114:115], v[132:133], 2, v[114:115]
	global_load_dwordx4 v[142:145], v[114:115], off nt
	global_load_dwordx4 v[146:149], v[114:115], off offset:16 nt
	global_load_dwordx4 v[154:157], v[114:115], off offset:512 nt
	global_load_dwordx4 v[158:161], v[114:115], off offset:528 nt
	s_waitcnt vmcnt(3)
	v_pk_fma_f32 v[112:113], v[112:113], 0.5, v[144:145] op_sel_hi:[1,0,1]
	v_pk_fma_f32 v[136:137], v[110:111], 0.5, v[142:143] op_sel_hi:[1,0,1]
	s_waitcnt vmcnt(2)
	v_pk_fma_f32 v[108:109], v[108:109], 0.5, v[148:149] op_sel_hi:[1,0,1]
	v_pk_fma_f32 v[110:111], v[106:107], 0.5, v[146:147] op_sel_hi:[1,0,1]
	s_waitcnt vmcnt(1)
	v_pk_fma_f32 v[104:105], v[104:105], 0.5, v[156:157] op_sel_hi:[1,0,1]
	v_pk_fma_f32 v[106:107], v[102:103], 0.5, v[154:155] op_sel_hi:[1,0,1]
	s_waitcnt vmcnt(0)
	v_pk_fma_f32 v[100:101], v[100:101], 0.5, v[160:161] op_sel_hi:[1,0,1]
	v_pk_fma_f32 v[102:103], v[98:99], 0.5, v[158:159] op_sel_hi:[1,0,1]
	v_mul_f32_e32 v98, v137, v137
	v_mul_f32_e32 v99, v113, v113
	v_mul_f32_e32 v139, v111, v111
	v_mul_f32_e32 v142, v109, v109
	v_mul_f32_e32 v143, v107, v107
	v_mul_f32_e32 v144, v105, v105
	v_mul_f32_e32 v145, v103, v103
	v_mul_f32_e32 v146, v101, v101
	v_fmac_f32_e32 v98, v136, v136
	v_fmac_f32_e32 v99, v112, v112
	v_fmac_f32_e32 v139, v110, v110
	v_fmac_f32_e32 v142, v108, v108
	v_fmac_f32_e32 v143, v106, v106
	v_fmac_f32_e32 v144, v104, v104
	v_fmac_f32_e32 v145, v102, v102
	v_fmac_f32_e32 v146, v100, v100
	v_add_f32_e32 v98, v98, v99
	v_add_f32_e32 v99, v139, v142
	v_add_f32_e32 v139, v143, v144
	v_add_f32_e32 v142, v145, v146
	v_add_f32_e32 v98, v98, v99
	v_add_f32_e32 v99, v139, v142
	v_add_f32_e32 v98, v98, v99
	ds_bpermute_b32 v99, v150, v98
	s_waitcnt lgkmcnt(0)
	v_add_f32_e32 v98, v98, v99
	ds_bpermute_b32 v99, v151, v98
	s_and_saveexec_b64 s[0:1], vcc
	s_cbranch_execz .LBB0_3468
	v_lshl_add_u32 v138, v138, 4, s5
	s_waitcnt lgkmcnt(0)
	v_add_f32_e32 v98, v98, v99
	ds_write_b32 v138, v98
.LBB0_3468:
	s_or_b64 exec, exec, s[0:1]
	v_or_b32_e32 v142, 32, v1
	v_add_u32_e32 v98, s3, v142
	s_waitcnt lgkmcnt(0)
	v_ashrrev_i32_e32 v99, 31, v98
	v_lshlrev_b64 v[98:99], 12, v[98:99]
	v_lshl_add_u64 v[98:99], s[26:27], 0, v[98:99]
	v_lshl_add_u64 v[98:99], v[132:133], 2, v[98:99]
	global_load_dwordx4 v[144:147], v[98:99], off nt
	global_load_dwordx4 v[154:157], v[98:99], off offset:16 nt
	global_load_dwordx4 v[158:161], v[98:99], off offset:512 nt
	global_load_dwordx4 v[162:165], v[98:99], off offset:528 nt
	s_waitcnt vmcnt(3)
	v_pk_fma_f32 v[96:97], v[96:97], 0.5, v[146:147] op_sel_hi:[1,0,1]
	v_pk_fma_f32 v[138:139], v[94:95], 0.5, v[144:145] op_sel_hi:[1,0,1]
	s_waitcnt vmcnt(2)
	v_pk_fma_f32 v[92:93], v[92:93], 0.5, v[156:157] op_sel_hi:[1,0,1]
	v_pk_fma_f32 v[94:95], v[90:91], 0.5, v[154:155] op_sel_hi:[1,0,1]
	s_waitcnt vmcnt(1)
	v_pk_fma_f32 v[88:89], v[88:89], 0.5, v[160:161] op_sel_hi:[1,0,1]
	v_pk_fma_f32 v[90:91], v[86:87], 0.5, v[158:159] op_sel_hi:[1,0,1]
	s_waitcnt vmcnt(0)
	v_pk_fma_f32 v[84:85], v[84:85], 0.5, v[164:165] op_sel_hi:[1,0,1]
	v_pk_fma_f32 v[86:87], v[82:83], 0.5, v[162:163] op_sel_hi:[1,0,1]
	v_mul_f32_e32 v82, v139, v139
	v_mul_f32_e32 v83, v97, v97
	v_mul_f32_e32 v143, v95, v95
	v_mul_f32_e32 v144, v93, v93
	v_mul_f32_e32 v145, v91, v91
	v_mul_f32_e32 v146, v89, v89
	v_mul_f32_e32 v147, v87, v87
	v_mul_f32_e32 v148, v85, v85
	v_fmac_f32_e32 v82, v138, v138
	v_fmac_f32_e32 v83, v96, v96
	v_fmac_f32_e32 v143, v94, v94
	v_fmac_f32_e32 v144, v92, v92
	v_fmac_f32_e32 v145, v90, v90
	v_fmac_f32_e32 v146, v88, v88
	v_fmac_f32_e32 v147, v86, v86
	v_fmac_f32_e32 v148, v84, v84
	v_add_f32_e32 v82, v82, v83
	v_add_f32_e32 v83, v143, v144
	v_add_f32_e32 v143, v145, v146
	v_add_f32_e32 v144, v147, v148
	v_add_f32_e32 v82, v82, v83
	v_add_f32_e32 v83, v143, v144
	v_add_f32_e32 v82, v82, v83
	ds_bpermute_b32 v83, v150, v82
	s_waitcnt lgkmcnt(0)
	v_add_f32_e32 v82, v82, v83
	ds_bpermute_b32 v83, v151, v82
	s_and_saveexec_b64 s[0:1], vcc
	s_cbranch_execz .LBB0_3470
	v_lshl_add_u32 v142, v142, 4, s5
	s_waitcnt lgkmcnt(0)
	v_add_f32_e32 v82, v82, v83
	ds_write_b32 v142, v82
.LBB0_3470:
	s_or_b64 exec, exec, s[0:1]
	v_or_b32_e32 v144, 48, v1
	v_add_u32_e32 v82, s3, v144
	s_waitcnt lgkmcnt(0)
	v_ashrrev_i32_e32 v83, 31, v82
	v_lshlrev_b64 v[82:83], 12, v[82:83]
	v_lshl_add_u64 v[82:83], s[26:27], 0, v[82:83]
	v_lshl_add_u64 v[82:83], v[132:133], 2, v[82:83]
	global_load_dwordx4 v[146:149], v[82:83], off nt
	global_load_dwordx4 v[154:157], v[82:83], off offset:16 nt
	global_load_dwordx4 v[158:161], v[82:83], off offset:512 nt
	global_load_dwordx4 v[162:165], v[82:83], off offset:528 nt
	s_waitcnt vmcnt(3)
	v_pk_fma_f32 v[80:81], v[80:81], 0.5, v[148:149] op_sel_hi:[1,0,1]
	v_pk_fma_f32 v[142:143], v[78:79], 0.5, v[146:147] op_sel_hi:[1,0,1]
	s_waitcnt vmcnt(2)
	v_pk_fma_f32 v[76:77], v[76:77], 0.5, v[156:157] op_sel_hi:[1,0,1]
	v_pk_fma_f32 v[78:79], v[74:75], 0.5, v[154:155] op_sel_hi:[1,0,1]
	s_waitcnt vmcnt(1)
	v_pk_fma_f32 v[72:73], v[72:73], 0.5, v[160:161] op_sel_hi:[1,0,1]
	v_pk_fma_f32 v[74:75], v[70:71], 0.5, v[158:159] op_sel_hi:[1,0,1]
	s_waitcnt vmcnt(0)
	v_pk_fma_f32 v[68:69], v[68:69], 0.5, v[164:165] op_sel_hi:[1,0,1]
	v_pk_fma_f32 v[70:71], v[66:67], 0.5, v[162:163] op_sel_hi:[1,0,1]
	v_mul_f32_e32 v66, v143, v143
	v_mul_f32_e32 v67, v81, v81
	v_mul_f32_e32 v145, v79, v79
	v_mul_f32_e32 v146, v77, v77
	v_mul_f32_e32 v147, v75, v75
	v_mul_f32_e32 v148, v73, v73
	v_mul_f32_e32 v149, v71, v71
	v_mul_f32_e32 v153, v69, v69
	v_fmac_f32_e32 v66, v142, v142
	v_fmac_f32_e32 v67, v80, v80
	v_fmac_f32_e32 v145, v78, v78
	v_fmac_f32_e32 v146, v76, v76
	v_fmac_f32_e32 v147, v74, v74
	v_fmac_f32_e32 v148, v72, v72
	v_fmac_f32_e32 v149, v70, v70
	v_fmac_f32_e32 v153, v68, v68
	v_add_f32_e32 v66, v66, v67
	v_add_f32_e32 v67, v145, v146
	v_add_f32_e32 v145, v147, v148
	v_add_f32_e32 v146, v149, v153
	v_add_f32_e32 v66, v66, v67
	v_add_f32_e32 v67, v145, v146
	v_add_f32_e32 v66, v66, v67
	ds_bpermute_b32 v67, v150, v66
	s_waitcnt lgkmcnt(0)
	v_add_f32_e32 v66, v66, v67
	ds_bpermute_b32 v67, v151, v66
	s_and_saveexec_b64 s[0:1], vcc
	s_cbranch_execz .LBB0_3472
	v_lshl_add_u32 v144, v144, 4, s5
	s_waitcnt lgkmcnt(0)
	v_add_f32_e32 v66, v66, v67
	ds_write_b32 v144, v66
.LBB0_3472:
	s_or_b64 exec, exec, s[0:1]
	v_add_u32_e32 v146, 0x80, v1
	v_add_u32_e32 v66, s3, v146
	s_waitcnt lgkmcnt(0)
	v_ashrrev_i32_e32 v67, 31, v66
	v_lshlrev_b64 v[66:67], 12, v[66:67]
	v_lshl_add_u64 v[66:67], s[26:27], 0, v[66:67]
	v_lshl_add_u64 v[66:67], v[132:133], 2, v[66:67]
	global_load_dwordx4 v[154:157], v[66:67], off nt
	global_load_dwordx4 v[158:161], v[66:67], off offset:16 nt
	global_load_dwordx4 v[162:165], v[66:67], off offset:512 nt
	global_load_dwordx4 v[166:169], v[66:67], off offset:528 nt
	s_waitcnt vmcnt(3)
	v_pk_fma_f32 v[64:65], v[64:65], 0.5, v[156:157] op_sel_hi:[1,0,1]
	v_pk_fma_f32 v[144:145], v[62:63], 0.5, v[154:155] op_sel_hi:[1,0,1]
	s_waitcnt vmcnt(2)
	v_pk_fma_f32 v[60:61], v[60:61], 0.5, v[160:161] op_sel_hi:[1,0,1]
	v_pk_fma_f32 v[62:63], v[58:59], 0.5, v[158:159] op_sel_hi:[1,0,1]
	s_waitcnt vmcnt(1)
	v_pk_fma_f32 v[56:57], v[56:57], 0.5, v[164:165] op_sel_hi:[1,0,1]
	v_pk_fma_f32 v[58:59], v[54:55], 0.5, v[162:163] op_sel_hi:[1,0,1]
	s_waitcnt vmcnt(0)
	v_pk_fma_f32 v[52:53], v[52:53], 0.5, v[168:169] op_sel_hi:[1,0,1]
	v_pk_fma_f32 v[54:55], v[50:51], 0.5, v[166:167] op_sel_hi:[1,0,1]
	v_mul_f32_e32 v50, v145, v145
	v_mul_f32_e32 v51, v65, v65
	v_mul_f32_e32 v147, v63, v63
	v_mul_f32_e32 v148, v61, v61
	v_mul_f32_e32 v149, v59, v59
	v_mul_f32_e32 v153, v57, v57
	v_mul_f32_e32 v154, v55, v55
	v_mul_f32_e32 v155, v53, v53
	v_fmac_f32_e32 v50, v144, v144
	v_fmac_f32_e32 v51, v64, v64
	v_fmac_f32_e32 v147, v62, v62
	v_fmac_f32_e32 v148, v60, v60
	v_fmac_f32_e32 v149, v58, v58
	v_fmac_f32_e32 v153, v56, v56
	v_fmac_f32_e32 v154, v54, v54
	v_fmac_f32_e32 v155, v52, v52
	v_add_f32_e32 v50, v50, v51
	v_add_f32_e32 v51, v147, v148
	v_add_f32_e32 v147, v149, v153
	v_add_f32_e32 v148, v154, v155
	v_add_f32_e32 v50, v50, v51
	v_add_f32_e32 v51, v147, v148
	v_add_f32_e32 v50, v50, v51
	ds_bpermute_b32 v51, v150, v50
	s_waitcnt lgkmcnt(0)
	v_add_f32_e32 v50, v50, v51
	ds_bpermute_b32 v51, v151, v50
	s_and_saveexec_b64 s[0:1], vcc
	s_cbranch_execz .LBB0_3474
	v_lshl_add_u32 v146, v146, 4, s5
	s_waitcnt lgkmcnt(0)
	v_add_f32_e32 v50, v50, v51
	ds_write_b32 v146, v50
.LBB0_3474:
	s_or_b64 exec, exec, s[0:1]
	v_add_u32_e32 v148, 0x90, v1
	v_add_u32_e32 v50, s3, v148
	s_waitcnt lgkmcnt(0)
	v_ashrrev_i32_e32 v51, 31, v50
	v_lshlrev_b64 v[50:51], 12, v[50:51]
	v_lshl_add_u64 v[50:51], s[26:27], 0, v[50:51]
	v_lshl_add_u64 v[50:51], v[132:133], 2, v[50:51]
	global_load_dwordx4 v[154:157], v[50:51], off nt
	global_load_dwordx4 v[158:161], v[50:51], off offset:16 nt
	global_load_dwordx4 v[162:165], v[50:51], off offset:512 nt
	global_load_dwordx4 v[166:169], v[50:51], off offset:528 nt
	s_waitcnt vmcnt(3)
	v_pk_fma_f32 v[48:49], v[48:49], 0.5, v[156:157] op_sel_hi:[1,0,1]
	v_pk_fma_f32 v[146:147], v[46:47], 0.5, v[154:155] op_sel_hi:[1,0,1]
	s_waitcnt vmcnt(2)
	v_pk_fma_f32 v[44:45], v[44:45], 0.5, v[160:161] op_sel_hi:[1,0,1]
	v_pk_fma_f32 v[46:47], v[42:43], 0.5, v[158:159] op_sel_hi:[1,0,1]
	s_waitcnt vmcnt(1)
	v_pk_fma_f32 v[40:41], v[40:41], 0.5, v[164:165] op_sel_hi:[1,0,1]
	v_pk_fma_f32 v[42:43], v[38:39], 0.5, v[162:163] op_sel_hi:[1,0,1]
	s_waitcnt vmcnt(0)
	v_pk_fma_f32 v[36:37], v[36:37], 0.5, v[168:169] op_sel_hi:[1,0,1]
	v_pk_fma_f32 v[38:39], v[34:35], 0.5, v[166:167] op_sel_hi:[1,0,1]
	v_mul_f32_e32 v34, v147, v147
	v_mul_f32_e32 v35, v49, v49
	v_mul_f32_e32 v149, v47, v47
	v_mul_f32_e32 v153, v45, v45
	v_mul_f32_e32 v154, v43, v43
	v_mul_f32_e32 v155, v41, v41
	v_mul_f32_e32 v156, v39, v39
	v_mul_f32_e32 v157, v37, v37
	v_fmac_f32_e32 v34, v146, v146
	v_fmac_f32_e32 v35, v48, v48
	v_fmac_f32_e32 v149, v46, v46
	v_fmac_f32_e32 v153, v44, v44
	v_fmac_f32_e32 v154, v42, v42
	v_fmac_f32_e32 v155, v40, v40
	v_fmac_f32_e32 v156, v38, v38
	v_fmac_f32_e32 v157, v36, v36
	v_add_f32_e32 v34, v34, v35
	v_add_f32_e32 v35, v149, v153
	v_add_f32_e32 v149, v154, v155
	v_add_f32_e32 v153, v156, v157
	v_add_f32_e32 v34, v34, v35
	v_add_f32_e32 v35, v149, v153
	v_add_f32_e32 v34, v34, v35
	ds_bpermute_b32 v35, v150, v34
	s_waitcnt lgkmcnt(0)
	v_add_f32_e32 v34, v34, v35
	ds_bpermute_b32 v35, v151, v34
	s_and_saveexec_b64 s[0:1], vcc
	s_cbranch_execz .LBB0_3476
	v_lshl_add_u32 v148, v148, 4, s5
	s_waitcnt lgkmcnt(0)
	v_add_f32_e32 v34, v34, v35
	ds_write_b32 v148, v34
.LBB0_3476:
	s_or_b64 exec, exec, s[0:1]
	v_add_u32_e32 v153, 0xa0, v1
	v_add_u32_e32 v34, s3, v153
	s_waitcnt lgkmcnt(0)
	v_ashrrev_i32_e32 v35, 31, v34
	v_lshlrev_b64 v[34:35], 12, v[34:35]
	v_lshl_add_u64 v[34:35], s[26:27], 0, v[34:35]
	v_lshl_add_u64 v[34:35], v[132:133], 2, v[34:35]
	global_load_dwordx4 v[154:157], v[34:35], off nt
	global_load_dwordx4 v[158:161], v[34:35], off offset:16 nt
	global_load_dwordx4 v[162:165], v[34:35], off offset:512 nt
	global_load_dwordx4 v[166:169], v[34:35], off offset:528 nt
	s_waitcnt vmcnt(3)
	v_pk_fma_f32 v[32:33], v[32:33], 0.5, v[156:157] op_sel_hi:[1,0,1]
	v_pk_fma_f32 v[148:149], v[30:31], 0.5, v[154:155] op_sel_hi:[1,0,1]
	s_waitcnt vmcnt(2)
	v_pk_fma_f32 v[28:29], v[28:29], 0.5, v[160:161] op_sel_hi:[1,0,1]
	v_pk_fma_f32 v[30:31], v[26:27], 0.5, v[158:159] op_sel_hi:[1,0,1]
	s_waitcnt vmcnt(1)
	v_pk_fma_f32 v[24:25], v[24:25], 0.5, v[164:165] op_sel_hi:[1,0,1]
	v_pk_fma_f32 v[26:27], v[22:23], 0.5, v[162:163] op_sel_hi:[1,0,1]
	s_waitcnt vmcnt(0)
	v_pk_fma_f32 v[20:21], v[20:21], 0.5, v[168:169] op_sel_hi:[1,0,1]
	v_pk_fma_f32 v[22:23], v[18:19], 0.5, v[166:167] op_sel_hi:[1,0,1]
	v_mul_f32_e32 v18, v149, v149
	v_mul_f32_e32 v19, v33, v33
	v_mul_f32_e32 v154, v31, v31
	v_mul_f32_e32 v155, v29, v29
	v_mul_f32_e32 v156, v27, v27
	v_mul_f32_e32 v157, v25, v25
	v_mul_f32_e32 v158, v23, v23
	v_mul_f32_e32 v159, v21, v21
	v_fmac_f32_e32 v18, v148, v148
	v_fmac_f32_e32 v19, v32, v32
	v_fmac_f32_e32 v154, v30, v30
	v_fmac_f32_e32 v155, v28, v28
	v_fmac_f32_e32 v156, v26, v26
	v_fmac_f32_e32 v157, v24, v24
	v_fmac_f32_e32 v158, v22, v22
	v_fmac_f32_e32 v159, v20, v20
	v_add_f32_e32 v18, v18, v19
	v_add_f32_e32 v19, v154, v155
	v_add_f32_e32 v154, v156, v157
	v_add_f32_e32 v155, v158, v159
	v_add_f32_e32 v18, v18, v19
	v_add_f32_e32 v19, v154, v155
	v_add_f32_e32 v18, v18, v19
	ds_bpermute_b32 v19, v150, v18
	s_waitcnt lgkmcnt(0)
	v_add_f32_e32 v18, v18, v19
	ds_bpermute_b32 v19, v151, v18
	s_and_saveexec_b64 s[0:1], vcc
	s_cbranch_execz .LBB0_3478
	v_lshl_add_u32 v153, v153, 4, s5
	s_waitcnt lgkmcnt(0)
	v_add_f32_e32 v18, v18, v19
	ds_write_b32 v153, v18
.LBB0_3478:
	s_or_b64 exec, exec, s[0:1]
	v_add_u32_e32 v153, 0xb0, v1
	v_add_u32_e32 v18, s3, v153
	s_waitcnt lgkmcnt(0)
	v_ashrrev_i32_e32 v19, 31, v18
	v_lshlrev_b64 v[18:19], 12, v[18:19]
	v_lshl_add_u64 v[18:19], s[26:27], 0, v[18:19]
	v_lshl_add_u64 v[18:19], v[132:133], 2, v[18:19]
	global_load_dwordx4 v[154:157], v[18:19], off nt
	global_load_dwordx4 v[158:161], v[18:19], off offset:16 nt
	global_load_dwordx4 v[162:165], v[18:19], off offset:512 nt
	global_load_dwordx4 v[166:169], v[18:19], off offset:528 nt
	s_waitcnt vmcnt(3)
	v_pk_fma_f32 v[16:17], v[16:17], 0.5, v[156:157] op_sel_hi:[1,0,1]
	v_pk_fma_f32 v[14:15], v[14:15], 0.5, v[154:155] op_sel_hi:[1,0,1]
	s_waitcnt vmcnt(2)
	v_pk_fma_f32 v[12:13], v[12:13], 0.5, v[160:161] op_sel_hi:[1,0,1]
	v_pk_fma_f32 v[10:11], v[10:11], 0.5, v[158:159] op_sel_hi:[1,0,1]
	s_waitcnt vmcnt(1)
	v_pk_fma_f32 v[8:9], v[8:9], 0.5, v[164:165] op_sel_hi:[1,0,1]
	v_pk_fma_f32 v[6:7], v[6:7], 0.5, v[162:163] op_sel_hi:[1,0,1]
	s_waitcnt vmcnt(0)
	v_pk_fma_f32 v[4:5], v[4:5], 0.5, v[168:169] op_sel_hi:[1,0,1]
	v_pk_fma_f32 v[2:3], v[2:3], 0.5, v[166:167] op_sel_hi:[1,0,1]
	v_mul_f32_e32 v154, v15, v15
	v_mul_f32_e32 v155, v17, v17
	v_mul_f32_e32 v156, v11, v11
	v_mul_f32_e32 v157, v13, v13
	v_mul_f32_e32 v158, v7, v7
	v_mul_f32_e32 v159, v9, v9
	v_mul_f32_e32 v160, v3, v3
	v_mul_f32_e32 v161, v5, v5
	v_fmac_f32_e32 v154, v14, v14
	v_fmac_f32_e32 v155, v16, v16
	v_fmac_f32_e32 v156, v10, v10
	v_fmac_f32_e32 v157, v12, v12
	v_fmac_f32_e32 v158, v6, v6
	v_fmac_f32_e32 v159, v8, v8
	v_fmac_f32_e32 v160, v2, v2
	v_fmac_f32_e32 v161, v4, v4
	v_add_f32_e32 v154, v154, v155
	v_add_f32_e32 v155, v156, v157
	v_add_f32_e32 v156, v158, v159
	v_add_f32_e32 v157, v160, v161
	v_add_f32_e32 v154, v154, v155
	v_add_f32_e32 v155, v156, v157
	v_add_f32_e32 v154, v154, v155
	ds_bpermute_b32 v150, v150, v154
	s_waitcnt lgkmcnt(0)
	v_add_f32_e32 v150, v154, v150
	ds_bpermute_b32 v151, v151, v150
	s_and_saveexec_b64 s[0:1], vcc
	s_cbranch_execz .LBB0_3480
	v_lshl_add_u32 v153, v153, 4, s5
	s_waitcnt lgkmcnt(0)
	v_add_f32_e32 v150, v150, v151
	ds_write_b32 v153, v150
